# plus loader waves each own 1-2 DMA pieces of every chunk; SGU epilogue loads batched (2 round trips instead of 4)
# baseline (speedup 1.0000x reference)
; #define GAS __attribute__((address_space(1)))
; __device__ __forceinline__ void sgu_job(LAS unsigned char* lds, const GAS float* Wh, const GAS float* sbias, const GAS float* VLN, GAS float* U, int m0, int h, int tid) {
;     ...
; #pragma unroll
;     for (int i = 0; i < 4; ++i) { const int t = t0 + i; const float bias = sbias[t]; GAS float* up = U + (size_t)(m0 + t) * 512 + h * 128 + d0;
;         f32x4 u0 = *(const GAS f32x4*)up, u1 = *(const GAS f32x4*)(up + 4);
;         u0.x *= acc[i][0] + bias; u0.y *= acc[i][1] + bias; u0.z *= acc[i][2] + bias; u0.w *= acc[i][3] + bias; u1.x *= acc[i][4] + bias; u1.y *= acc[i][5] + bias; u1.z *= acc[i][6] + bias; u1.w *= acc[i][7] + bias;
;         *(GAS f32x4*)up = u0; *(GAS f32x4*)(up + 4) = u1; }
.LBB0_621:
	s_or_b64 exec, exec, s[2:3]
	s_lshl_b32 s2, s23, 7
	s_or_b32 s82, s2, s22
	s_lshl_b64 s[0:1], s[82:83], 2
	s_add_u32 s0, s18, s0
	v_add_u32_e32 v148, s17, v2
	s_addc_u32 s1, s19, s1
	s_lshl_b32 s82, s2, 2
	v_ashrrev_i32_e32 v149, 31, v148
	v_lshl_add_u64 v[44:45], v[6:7], 0, s[82:83]
	v_lshl_add_u64 v[156:157], v[2:3], 2, s[0:1]
	v_lshlrev_b64 v[148:149], 11, v[148:149]
	global_load_dword v158, v[156:157], off
	v_lshl_add_u64 v[160:161], v[44:45], 0, v[148:149]
	global_load_dwordx4 v[148:151], v[160:161], off offset:16
	global_load_dwordx4 v[152:155], v[160:161], off
	v_add_u32_e32 v162, s17, v16
	v_ashrrev_i32_e32 v163, 31, v162
	v_lshlrev_b64 v[162:163], 11, v[162:163]
	v_lshl_add_u64 v[162:163], v[44:45], 0, v[162:163]
	global_load_dword v159, v[156:157], off offset:4
	global_load_dwordx4 v[164:167], v[162:163], off offset:16
	global_load_dwordx4 v[168:171], v[162:163], off
	s_waitcnt vmcnt(5)
	v_pk_add_f32 v[42:43], v[42:43], v[158:159] op_sel_hi:[1,0]
	v_pk_add_f32 v[40:41], v[40:41], v[158:159] op_sel_hi:[1,0]
	v_pk_add_f32 v[36:37], v[36:37], v[158:159] op_sel_hi:[1,0]
	v_pk_add_f32 v[38:39], v[38:39], v[158:159] op_sel_hi:[1,0]
	s_waitcnt vmcnt(3)
	v_pk_mul_f32 v[40:41], v[40:41], v[152:153]
	v_pk_mul_f32 v[42:43], v[42:43], v[154:155]
	v_pk_mul_f32 v[36:37], v[36:37], v[148:149]
	v_pk_mul_f32 v[38:39], v[38:39], v[150:151]
	global_store_dwordx4 v[160:161], v[40:43], off
	global_store_dwordx4 v[160:161], v[36:39], off offset:16
	s_waitcnt vmcnt(2)
	v_pk_add_f32 v[34:35], v[34:35], v[158:159] op_sel:[0,1]
	v_pk_add_f32 v[32:33], v[32:33], v[158:159] op_sel:[0,1]
	v_pk_add_f32 v[30:31], v[30:31], v[158:159] op_sel:[0,1]
	v_pk_add_f32 v[28:29], v[28:29], v[158:159] op_sel:[0,1]
	v_pk_mul_f32 v[168:169], v[34:35], v[168:169]
	v_pk_mul_f32 v[170:171], v[32:33], v[170:171]
	v_pk_mul_f32 v[164:165], v[30:31], v[164:165]
	v_pk_mul_f32 v[166:167], v[28:29], v[166:167]
	global_store_dwordx4 v[162:163], v[168:171], off
	global_store_dwordx4 v[162:163], v[164:167], off offset:16
	v_add_u32_e32 v160, s17, v110
	v_ashrrev_i32_e32 v161, 31, v160
	v_lshlrev_b64 v[160:161], 11, v[160:161]
	v_lshl_add_u64 v[160:161], v[44:45], 0, v[160:161]
	global_load_dword v158, v[156:157], off offset:8
	global_load_dwordx4 v[148:151], v[160:161], off offset:16
	global_load_dwordx4 v[152:155], v[160:161], off
	v_lshl_add_u64 v[172:173], v[4:5], 2, s[0:1]
	global_load_dword v159, v[172:173], off
	v_add_u32_e32 v172, s17, v4
	v_ashrrev_i32_e32 v173, 31, v172
	v_lshlrev_b64 v[172:173], 11, v[172:173]
	v_lshl_add_u64 v[172:173], v[44:45], 0, v[172:173]
	global_load_dwordx4 v[28:31], v[172:173], off offset:16
	global_load_dwordx4 v[32:35], v[172:173], off
	v_readlane_b32 s0, v252, 15
	s_add_i32 s16, s16, s0
	s_cmpk_lt_i32 s16, 0x100
	s_waitcnt vmcnt(3)
	v_pk_add_f32 v[26:27], v[26:27], v[158:159] op_sel_hi:[1,0]
	v_pk_add_f32 v[24:25], v[24:25], v[158:159] op_sel_hi:[1,0]
	v_pk_add_f32 v[22:23], v[22:23], v[158:159] op_sel_hi:[1,0]
	v_pk_add_f32 v[20:21], v[20:21], v[158:159] op_sel_hi:[1,0]
	v_pk_mul_f32 v[152:153], v[26:27], v[152:153]
	v_pk_mul_f32 v[154:155], v[24:25], v[154:155]
	v_pk_mul_f32 v[148:149], v[22:23], v[148:149]
	v_pk_mul_f32 v[150:151], v[20:21], v[150:151]
	global_store_dwordx4 v[160:161], v[152:155], off
	global_store_dwordx4 v[160:161], v[148:151], off offset:16
	s_waitcnt vmcnt(2)
	v_pk_add_f32 v[18:19], v[18:19], v[158:159] op_sel:[0,1]
	v_pk_add_f32 v[14:15], v[14:15], v[158:159] op_sel:[0,1]
	v_pk_add_f32 v[12:13], v[12:13], v[158:159] op_sel:[0,1]
	v_pk_add_f32 v[10:11], v[10:11], v[158:159] op_sel:[0,1]
	v_pk_mul_f32 v[32:33], v[18:19], v[32:33]
	v_pk_mul_f32 v[34:35], v[14:15], v[34:35]
	v_pk_mul_f32 v[28:29], v[12:13], v[28:29]
	v_pk_mul_f32 v[30:31], v[10:11], v[30:31]
	global_store_dwordx4 v[172:173], v[32:35], off
	global_store_dwordx4 v[172:173], v[28:31], off offset:16
	s_barrier
	s_cbranch_scc0 .LBB0_626

; #define GAS __attribute__((address_space(1)))
; #define R4_ISSUE(cc, slot) do { const GAS float* g_ = gp + (size_t)(cc) * 2048; LAS float* l_ = ring + (slot) * 1536; _Pragma("unroll") for (int i_ = 0; i_ < 6; ++i_) \
;         __builtin_amdgcn_global_load_lds((const GAS unsigned*)(g_ + off[i_]), (LAS unsigned*)(l_ + i_ * 256), 16, 0, 0); } while (0)
; #define R4_LOAD(o, sb_) do { const LAS float* sb = (sb_); (o).r = *(const LAS f32x4*)(sb + cgp * 4); (o).w = *(const LAS f32x4*)(sb + 64 + cgp * 4); (o).k = *(const LAS f32x4*)(sb + 128 + cgp * 4); \
;         (o).a = *(const LAS f32x4*)(sb + 256 + cgp * 4); (o).b = *(const LAS f32x4*)(sb + 320 + cgp * 4); (o).vv = sb[192 + rq * 4 + rl]; asm volatile("" ::: "memory"); } while (0)
; __device__ __forceinline__ void rwkv_prompt_wave4(LAS float* ring, const GAS float* RW, int mbase, int h, int rq, GAS float* Sout, GAS float* YR, int lane) {
;     ...
;     unsigned off[6];
; #pragma unroll
;     for (int i = 0; i < 6; ++i) { const int e = i * 256 + lane * 4, st = e / 384, rem = e - st * 384; off[i] = (unsigned)((rem >> 6) * SZ + st * 512 + (rem & 63)); }
;     const GAS float* gp = RW + (size_t)mbase * 512 + h * 64;
;     constexpr int NCH = SEQ / 4;
;     ...
;     for (int cc = 0; cc < 3; ++cc) R4_ISSUE(cc, cc);
;     float ykeep = 0.f;
;     R4Ops oA, oB, oC, oD;
;     asm volatile("s_waitcnt vmcnt(12)" ::: "memory");
;     R4_LOAD(oA, ring); R4_LOAD(oB, ring + 384);
;     for (int ci = 0; ci < NCH; ++ci) {
;         { const int cn = ci + 3; const int cl = cn < NCH ? cn : NCH - 1; R4_ISSUE(cl, cn % R4_NS); }
.Lld_entry:
	s_cmp_lt_u32 s24, 4
	s_cbranch_scc1 .LBB0_709
	v_readlane_b32 s0, v251, 4
	s_load_dwordx2 s[6:7], s[68:69], 0x138
	s_nop 3
	s_sub_u32 s1, s24, 4
	s_lshl_b32 s2, s0, 2
	s_lshr_b32 s3, s2, 7
	s_bfe_u32 s12, s2, 0x30004
	v_and_b32_e32 v0, 63, v195
	v_lshlrev_b32_e32 v0, 2, v0
	s_lshl_b32 s16, s1, 8
	v_add_u32_e32 v1, s16, v0
	v_lshrrev_b32_e32 v2, 7, v1
	v_mul_u32_u24_e32 v3, 11, v2
	v_lshrrev_b32_e32 v3, 5, v3
	v_mul_u32_u24_e32 v4, 0x180, v3
	v_sub_u32_e32 v4, v1, v4
	v_lshrrev_b32_e32 v5, 6, v4
	v_and_b32_e32 v6, 63, v4
	v_lshlrev_b32_e32 v6, 2, v6
	v_lshl_add_u32 v6, v3, 11, v6
	s_mov_b32 s8, 0x1100000
	v_mul_lo_u32 v5, v5, s8
	v_add_u32_e32 v20, v5, v6
	v_add_u32_e32 v1, 0x400, v1
	v_lshrrev_b32_e32 v2, 7, v1
	v_mul_u32_u24_e32 v3, 11, v2
	v_lshrrev_b32_e32 v3, 5, v3
	v_mul_u32_u24_e32 v4, 0x180, v3
	v_sub_u32_e32 v4, v1, v4
	v_lshrrev_b32_e32 v5, 6, v4
	v_and_b32_e32 v6, 63, v4
	v_lshlrev_b32_e32 v6, 2, v6
	v_lshl_add_u32 v6, v3, 11, v6
	s_mov_b32 s8, 0x1100000
	v_mul_lo_u32 v5, v5, s8
	v_add_u32_e32 v21, v5, v6
	s_waitcnt lgkmcnt(0)
	s_add_u32 s4, s6, 0x1ad00000
	s_addc_u32 s5, s7, 0
	s_lshl_b32 s3, s3, 22
	s_add_u32 s4, s4, s3
	s_addc_u32 s5, s5, 0
	s_lshl_b32 s12, s12, 8
	s_add_u32 s4, s4, s12
	s_addc_u32 s5, s5, 0
	s_lshl_b32 s16, s1, 10
	s_mov_b32 s14, 0
	s_mov_b32 s17, 0
	s_mov_b32 s18, 0
.Lld_issue:
	s_min_u32 s3, s14, 0x1ff
	s_lshl_b32 s3, s3, 13
	s_add_u32 s8, s4, s3
	s_addc_u32 s9, s5, 0
	s_and_b32 s2, s14, 15
	s_mul_i32 s2, s2, 0x1800
	s_add_i32 s2, s2, s16
	s_mov_b32 m0, s2
	s_nop 0
	global_load_lds_dwordx4 v20, s[8:9]
	s_cmp_ge_u32 s1, 2
	s_cbranch_scc1 .Lld_one
	s_add_i32 m0, s2, 0x1000
	s_nop 0
	global_load_lds_dwordx4 v21, s[8:9]
.Lld_one:
	s_add_u32 s14, s14, 1
	s_cmp_eq_u32 s17, 1
	s_cbranch_scc1 .Lld_next
	s_cmp_lt_u32 s14, 12
	s_cbranch_scc1 .Lld_issue
	s_mov_b32 s17, 1
.Lld_loop:
	s_cmp_ge_u32 s1, 2
	s_cbranch_scc1 .Lld_w1
	s_waitcnt vmcnt(22)
	s_branch .Lld_bar
.Lld_w1:
	s_waitcnt vmcnt(11)
.Lld_bar:
	s_barrier
	s_branch .Lld_issue
.Lld_next:
	s_add_u32 s18, s18, 1
	s_cmp_le_u32 s18, 0x200
	s_cbranch_scc1 .Lld_loop
	s_waitcnt vmcnt(0)
